# MLA epilogue: all eight gate loads issued together (one round trip instead of three batches), counted waits that only retired them dropped
# speedup vs baseline: 1.0033x; 1.0008x over previous
.LBB0_541:
	s_or_b32 s10, s78, 3
	s_mul_hi_u32 s54, s10, 0x2aaaaaab
	s_mul_i32 s54, s54, 6
	s_sub_i32 s10, s10, s54
	s_mulk_i32 s10, 0x5000
	v_add_u32_e32 v0, s10, v106
	ds_read_b64_tr_b16 v[58:59], v0 offset:12288
	ds_read_b64_tr_b16 v[60:61], v0 offset:12800
	ds_read_b64_tr_b16 v[62:63], v0 offset:13312
	ds_read_b64_tr_b16 v[64:65], v0 offset:13824
	ds_read_b64_tr_b16 v[66:67], v0 offset:14336
	ds_read_b64_tr_b16 v[68:69], v0 offset:14848
	ds_read_b64_tr_b16 v[70:71], v0 offset:15360
	ds_read_b64_tr_b16 v[72:73], v0 offset:15872
	ds_read_b64_tr_b16 v[74:75], v0 offset:16384
	ds_read_b64_tr_b16 v[76:77], v0 offset:16896
	ds_read_b64_tr_b16 v[78:79], v0 offset:17408
	ds_read_b64_tr_b16 v[80:81], v0 offset:17920
	ds_read_b64_tr_b16 v[98:99], v0 offset:18432
	ds_read_b64_tr_b16 v[100:101], v0 offset:18944
	ds_read_b64_tr_b16 v[102:103], v0 offset:19456
	ds_read_b64_tr_b16 v[104:105], v0 offset:19968
	v_mov_b32_e32 v0, v186
	s_waitcnt lgkmcnt(0)
	s_barrier
	v_mov_b32_e32 v53, s53
	v_ashrrev_i32_e32 v50, 1, v0
	v_and_b32_e32 v50, 0xffffffe0, v50
	v_and_or_b32 v52, v0, 31, s19
	v_ashrrev_i32_e32 v51, 31, v50
	v_or_b32_e32 v52, s52, v52
	v_lshl_add_u64 v[50:51], v[52:53], 0, v[50:51]
	v_mov_b64_e32 v[52:53], s[16:17]
	v_mad_u64_u32 v[52:53], s[52:53], v50, s66, v[52:53]
	v_mad_i32_i24 v53, v51, s66, v53
	s_mov_b32 s19, s11
	v_lshrrev_b32_e32 v0, 2, v0
	v_lshl_add_u64 v[52:53], v[52:53], 0, s[18:19]
	v_and_b32_e32 v0, 8, v0
	v_lshl_add_u64 v[112:113], v[52:53], 0, v[0:1]
	s_movk_i32 s10, 0x1000
	v_add_co_u32_e32 v52, vcc, s10, v112
	v_cvt_pk_bf16_f32 v108, v82, v83
	s_nop 0
	v_addc_co_u32_e32 v53, vcc, 0, v113, vcc
	global_load_dwordx2 v[140:141], v[52:53], off offset:912
	global_load_dwordx2 v[142:143], v[52:53], off offset:928
	global_load_dwordx2 v[144:145], v[52:53], off offset:944
	global_load_dwordx2 v[146:147], v[52:53], off offset:848
	global_load_dwordx2 v[148:149], v[52:53], off offset:864
	global_load_dwordx2 v[150:151], v[52:53], off offset:880
	global_load_dwordx2 v[152:153], v[52:53], off offset:896
	global_load_dwordx2 v[52:53], v[52:53], off offset:832
	v_cvt_pk_bf16_f32 v109, v84, v85
	v_cvt_pk_bf16_f32 v110, v86, v87
	v_cvt_pk_bf16_f32 v111, v88, v89
	v_add_f32_e32 v57, v82, v34
	v_add_f32_e32 v82, v83, v35
	s_waitcnt lgkmcnt(14)
	v_mfma_f32_32x32x16_bf16 v[18:33], v[58:61], v[108:111], v[18:33]
	v_add_f32_e32 v83, v84, v36
	v_add_f32_e32 v84, v85, v37
	v_add_f32_e32 v85, v86, v38
	v_cvt_pk_bf16_f32 v34, v34, v35
	v_cvt_pk_bf16_f32 v35, v36, v37
	v_cvt_pk_bf16_f32 v36, v38, v39
	v_add_f32_e32 v38, 0, v57
	s_waitcnt lgkmcnt(6)
	v_mfma_f32_32x32x16_bf16 v[2:17], v[74:77], v[108:111], v[2:17]
	v_cvt_pk_bf16_f32 v58, v90, v91
	v_cvt_pk_bf16_f32 v59, v92, v93
	v_cvt_pk_bf16_f32 v60, v94, v95
	v_cvt_pk_bf16_f32 v61, v96, v97
	v_add_f32_e32 v38, v82, v38
	v_add_f32_e32 v38, v83, v38
	v_add_f32_e32 v38, v84, v38
	v_mfma_f32_32x32x16_bf16 v[18:33], v[62:65], v[58:61], v[18:33]
	v_add_f32_e32 v86, v87, v39
	v_add_f32_e32 v38, v85, v38
	v_add_f32_e32 v87, v88, v40
	v_add_f32_e32 v38, v86, v38
	v_add_f32_e32 v88, v89, v41
	v_add_f32_e32 v38, v87, v38
	v_add_f32_e32 v74, v90, v42
	s_waitcnt lgkmcnt(4)
	v_mfma_f32_32x32x16_bf16 v[2:17], v[78:81], v[58:61], v[2:17]
	v_add_f32_e32 v38, v88, v38
	v_add_f32_e32 v75, v91, v43
	v_add_f32_e32 v38, v74, v38
	v_add_f32_e32 v76, v92, v44
	v_cvt_pk_bf16_f32 v37, v40, v41
	v_add_f32_e32 v38, v75, v38
	v_add_f32_e32 v77, v93, v45
	v_mfma_f32_32x32x16_bf16 v[18:33], v[66:69], v[34:37], v[18:33]
	v_add_f32_e64 v62, v94, v46
	v_add_f32_e64 v63, v95, v47
	v_add_f32_e64 v64, v96, v48
	v_add_f32_e64 v65, v97, v49
	v_cvt_pk_bf16_f32 v41, v44, v45
	v_cvt_pk_bf16_f32 v40, v42, v43
	v_cvt_pk_bf16_f32 v42, v46, v47
	v_cvt_pk_bf16_f32 v43, v48, v49
	s_waitcnt vmcnt(0)
	v_lshlrev_b32_e32 v57, 16, v52
	s_waitcnt lgkmcnt(2)
	v_mfma_f32_32x32x16_bf16 v[2:17], v[98:101], v[34:37], v[2:17]
	v_add_f32_e32 v34, v76, v38
	v_add_f32_e32 v34, v77, v34
	v_add_f32_e32 v34, v62, v34
	v_add_f32_e32 v34, v63, v34
	v_add_f32_e32 v34, v64, v34
	v_add_f32_e32 v34, v65, v34
	v_add_f32_e32 v34, v107, v34
	v_mov_b32_e32 v35, v34
	s_nop 1
	v_permlane32_swap_b32_e32 v34, v35
	v_add_f32_e32 v38, v34, v35
	v_div_scale_f32 v34, s[52:53], v38, v38, 1.0
	v_rcp_f32_e32 v39, v34
	s_mov_b64 s[52:53], 0x1340
	v_and_b32_e32 v52, 0xffff0000, v52
	v_mul_f32_e32 v48, 0xbfb8aa3b, v57
	v_fma_f32 v35, -v34, v39, 1.0
	v_fmac_f32_e32 v39, v35, v39
	v_div_scale_f32 v35, vcc, 1.0, v38, 1.0
	v_mul_f32_e32 v44, v35, v39
	v_fma_f32 v36, -v34, v44, v35
	v_fmac_f32_e32 v44, v36, v39
	v_fma_f32 v45, -v34, v44, v35
	v_lshl_add_u64 v[34:35], v[112:113], 0, s[52:53]
	v_mul_f32_e32 v49, 0xbfb8aa3b, v52
	v_mfma_f32_32x32x16_bf16 v[18:33], v[70:73], v[40:43], v[18:33]
	v_exp_f32_e32 v48, v48
	v_exp_f32_e32 v49, v49
	v_div_fmas_f32 v39, v45, v39, v44
	v_div_fixup_f32 v38, v39, v38, 1.0
	v_pk_add_f32 v[44:45], v[48:49], 1.0 op_sel_hi:[1,0]
	s_nop 0
	v_div_scale_f32 v39, s[52:53], v45, v45, v52
	s_waitcnt lgkmcnt(0)
	v_mfma_f32_32x32x16_bf16 v[2:17], v[102:105], v[40:43], v[2:17]
	s_nop 7
	v_mov_b32_e32 v36, v140
	v_mov_b32_e32 v37, v141
	v_mov_b32_e32 v40, v142
	v_mov_b32_e32 v41, v143
	v_mov_b32_e32 v42, v144
	v_mov_b32_e32 v43, v145
	v_mov_b32_e32 v46, v146
	v_mov_b32_e32 v47, v147
	v_rcp_f32_e32 v58, v39
	v_lshlrev_b64 v[48:49], 11, v[50:51]
	v_pk_mul_f32 v[18:19], v[18:19], v[38:39] op_sel_hi:[1,0]
	v_lshl_add_u64 v[48:49], s[48:49], 0, v[48:49]
	v_fma_f32 v50, -v39, v58, 1.0
	v_fmac_f32_e32 v58, v50, v58
	v_div_scale_f32 v50, vcc, v52, v45, v52
	v_mul_f32_e32 v51, v50, v58
	v_fma_f32 v59, -v39, v51, v50
	v_fmac_f32_e32 v51, v59, v58
	v_div_scale_f32 v59, s[52:53], v44, v44, v57
	v_rcp_f32_e32 v60, v59
	v_fma_f32 v39, -v39, v51, v50
	v_div_fmas_f32 v39, v39, v58, v51
	v_div_fixup_f32 v45, v39, v45, v52
	v_fma_f32 v39, -v59, v60, 1.0
	v_fmac_f32_e32 v60, v39, v60
	v_div_scale_f32 v39, vcc, v57, v44, v57
	v_mul_f32_e32 v52, v39, v60
	v_fma_f32 v50, -v59, v52, v39
	v_lshlrev_b32_e32 v58, 16, v53
	v_and_b32_e32 v53, 0xffff0000, v53
	v_fmac_f32_e32 v52, v50, v60
	v_mul_f32_e32 v50, 0xbfb8aa3b, v58
	v_mul_f32_e32 v51, 0xbfb8aa3b, v53
	v_exp_f32_e32 v50, v50
	v_exp_f32_e32 v51, v51
	v_fma_f32 v39, -v59, v52, v39
	v_div_fmas_f32 v39, v39, v60, v52
	v_div_fixup_f32 v44, v39, v44, v57
	v_pk_add_f32 v[50:51], v[50:51], 1.0 op_sel_hi:[1,0]
	v_pk_mul_f32 v[20:21], v[20:21], v[38:39] op_sel_hi:[1,0]
	v_div_scale_f32 v52, s[52:53], v51, v51, v53
	v_rcp_f32_e32 v59, v52
	v_pk_mul_f32 v[18:19], v[18:19], v[44:45]
	v_fma_f32 v39, -v52, v59, 1.0
	v_fmac_f32_e32 v59, v39, v59
	v_div_scale_f32 v39, vcc, v53, v51, v53
	v_mul_f32_e32 v44, v39, v59
	v_fma_f32 v45, -v52, v44, v39
	v_fmac_f32_e32 v44, v45, v59
	v_fma_f32 v39, -v52, v44, v39
	v_div_scale_f32 v52, s[52:53], v50, v50, v58
	v_rcp_f32_e32 v57, v52
	v_div_fmas_f32 v39, v39, v59, v44
	v_div_fixup_f32 v45, v39, v51, v53
	v_fma_f32 v39, -v52, v57, 1.0
	v_fmac_f32_e32 v57, v39, v57
	v_div_scale_f32 v39, vcc, v58, v50, v58
	v_mul_f32_e32 v44, v39, v57
	v_fma_f32 v51, -v52, v44, v39
	v_fmac_f32_e32 v44, v51, v57
	v_fma_f32 v39, -v52, v44, v39
	v_div_fmas_f32 v39, v39, v57, v44
	v_div_fixup_f32 v44, v39, v50, v58
	v_mov_b32_e32 v50, v148
	v_mov_b32_e32 v51, v149
	v_mov_b32_e32 v52, v150
	v_mov_b32_e32 v53, v151
	s_nop 0
	v_mov_b32_e32 v34, v152
	v_mov_b32_e32 v35, v153
	v_pk_mul_f32 v[20:21], v[20:21], v[44:45]
	v_cvt_pk_bf16_f32 v44, v18, v19
	v_cvt_pk_bf16_f32 v45, v20, v21
	v_lshl_add_u64 v[18:19], v[48:49], 0, v[0:1]
	global_store_dwordx2 v[18:19], v[44:45], off offset:1024
	v_lshlrev_b32_e32 v39, 16, v46
	v_and_b32_e32 v46, 0xffff0000, v46
	v_mul_f32_e32 v57, 0xbfb8aa3b, v39
	v_exp_f32_e32 v58, v57
	v_mul_f32_e32 v57, 0xbfb8aa3b, v46
	v_exp_f32_e32 v59, v57
	v_pk_mul_f32 v[22:23], v[22:23], v[38:39] op_sel_hi:[1,0]
	v_pk_add_f32 v[20:21], v[58:59], 1.0 op_sel_hi:[1,0]
	s_nop 0
	v_div_scale_f32 v57, s[52:53], v21, v21, v46
	v_rcp_f32_e32 v58, v57
	v_div_scale_f32 v48, s[52:53], v20, v20, v39
	v_rcp_f32_e32 v49, v48
	v_fma_f32 v0, -v57, v58, 1.0
	v_fmac_f32_e32 v58, v0, v58
	v_div_scale_f32 v0, vcc, v46, v21, v46
	v_mul_f32_e32 v44, v0, v58
	v_fma_f32 v45, -v57, v44, v0
	v_fmac_f32_e32 v44, v45, v58
	v_fma_f32 v0, -v57, v44, v0
	v_div_fmas_f32 v0, v0, v58, v44
	v_div_fixup_f32 v21, v0, v21, v46
	v_fma_f32 v0, -v48, v49, 1.0
	v_fmac_f32_e32 v49, v0, v49
	v_div_scale_f32 v0, vcc, v39, v20, v39
	v_mul_f32_e32 v46, v0, v49
	v_fma_f32 v44, -v48, v46, v0
	v_lshlrev_b32_e32 v57, 16, v47
	v_and_b32_e32 v47, 0xffff0000, v47
	v_fmac_f32_e32 v46, v44, v49
	v_mul_f32_e32 v44, 0xbfb8aa3b, v57
	v_mul_f32_e32 v45, 0xbfb8aa3b, v47
	v_exp_f32_e32 v44, v44
	v_exp_f32_e32 v45, v45
	v_fma_f32 v0, -v48, v46, v0
	v_div_fmas_f32 v0, v0, v49, v46
	v_div_fixup_f32 v20, v0, v20, v39
	v_pk_add_f32 v[44:45], v[44:45], 1.0 op_sel_hi:[1,0]
	v_pk_mul_f32 v[20:21], v[22:23], v[20:21]
	v_div_scale_f32 v46, s[52:53], v45, v45, v47
	v_rcp_f32_e32 v48, v46
	v_pk_mul_f32 v[22:23], v[24:25], v[38:39] op_sel_hi:[1,0]
	v_div_scale_f32 v39, s[52:53], v44, v44, v57
	v_fma_f32 v0, -v46, v48, 1.0
	v_fmac_f32_e32 v48, v0, v48
	v_div_scale_f32 v0, vcc, v47, v45, v47
	v_mul_f32_e32 v24, v0, v48
	v_fma_f32 v25, -v46, v24, v0
	v_fmac_f32_e32 v24, v25, v48
	v_fma_f32 v0, -v46, v24, v0
	v_rcp_f32_e32 v46, v39
	v_div_fmas_f32 v0, v0, v48, v24
	v_div_fixup_f32 v25, v0, v45, v47
	v_cvt_pk_bf16_f32 v20, v20, v21
	v_fma_f32 v0, -v39, v46, 1.0
	v_fmac_f32_e32 v46, v0, v46
	v_div_scale_f32 v0, vcc, v57, v44, v57
	v_mul_f32_e32 v24, v0, v46
	v_fma_f32 v45, -v39, v24, v0
	v_fmac_f32_e32 v24, v45, v46
	v_fma_f32 v0, -v39, v24, v0
	v_lshlrev_b32_e32 v39, 16, v50
	v_div_fmas_f32 v0, v0, v46, v24
	v_and_b32_e32 v45, 0xffff0000, v50
	v_mul_f32_e32 v24, 0xbfb8aa3b, v39
	v_exp_f32_e32 v46, v24
	v_mul_f32_e32 v24, 0xbfb8aa3b, v45
	v_exp_f32_e32 v47, v24
	v_div_fixup_f32 v24, v0, v44, v57
	v_pk_mul_f32 v[22:23], v[22:23], v[24:25]
	v_pk_add_f32 v[24:25], v[46:47], 1.0 op_sel_hi:[1,0]
	s_nop 0
	v_div_scale_f32 v0, s[52:53], v25, v25, v45
	v_rcp_f32_e32 v44, v0
	v_cvt_pk_bf16_f32 v21, v22, v23
	global_store_dwordx2 v[18:19], v[20:21], off offset:1040
	v_pk_mul_f32 v[20:21], v[26:27], v[38:39] op_sel_hi:[1,0]
	v_fma_f32 v22, -v0, v44, 1.0
	v_fmac_f32_e32 v44, v22, v44
	v_div_scale_f32 v22, vcc, v45, v25, v45
	v_mul_f32_e32 v23, v22, v44
	v_fma_f32 v26, -v0, v23, v22
	v_fmac_f32_e32 v23, v26, v44
	v_fma_f32 v0, -v0, v23, v22
	v_div_scale_f32 v22, s[52:53], v24, v24, v39
	v_rcp_f32_e32 v46, v22
	v_div_fmas_f32 v0, v0, v44, v23
	v_div_fixup_f32 v23, v0, v25, v45
	v_lshlrev_b32_e32 v44, 16, v51
	v_fma_f32 v0, -v22, v46, 1.0
	v_fmac_f32_e32 v46, v0, v46
	v_div_scale_f32 v0, vcc, v39, v24, v39
	v_mul_f32_e32 v25, v0, v46
	v_fma_f32 v26, -v22, v25, v0
	v_and_b32_e32 v45, 0xffff0000, v51
	v_fmac_f32_e32 v25, v26, v46
	v_mul_f32_e32 v26, 0xbfb8aa3b, v44
	v_mul_f32_e32 v27, 0xbfb8aa3b, v45
	v_exp_f32_e32 v26, v26
	v_exp_f32_e32 v27, v27
	v_fma_f32 v0, -v22, v25, v0
	v_div_fmas_f32 v0, v0, v46, v25
	v_div_fixup_f32 v22, v0, v24, v39
	v_pk_add_f32 v[26:27], v[26:27], 1.0 op_sel_hi:[1,0]
	v_pk_mul_f32 v[20:21], v[20:21], v[22:23]
	v_div_scale_f32 v25, s[52:53], v27, v27, v45
	v_rcp_f32_e32 v46, v25
	v_pk_mul_f32 v[22:23], v[28:29], v[38:39] op_sel_hi:[1,0]
	v_lshlrev_b32_e32 v39, 16, v52
	v_cvt_pk_bf16_f32 v20, v20, v21
	v_fma_f32 v0, -v25, v46, 1.0
	v_fmac_f32_e32 v46, v0, v46
	v_div_scale_f32 v0, vcc, v45, v27, v45
	v_mul_f32_e32 v24, v0, v46
	v_fma_f32 v28, -v25, v24, v0
	v_fmac_f32_e32 v24, v28, v46
	v_div_scale_f32 v28, s[52:53], v26, v26, v44
	v_rcp_f32_e32 v29, v28
	v_fma_f32 v0, -v25, v24, v0
	v_div_fmas_f32 v0, v0, v46, v24
	v_div_fixup_f32 v25, v0, v27, v45
	v_fma_f32 v0, -v28, v29, 1.0
	v_fmac_f32_e32 v29, v0, v29
	v_div_scale_f32 v0, vcc, v44, v26, v44
	v_mul_f32_e32 v24, v0, v29
	v_fma_f32 v27, -v28, v24, v0
	v_fmac_f32_e32 v24, v27, v29
	v_fma_f32 v0, -v28, v24, v0
	v_div_fmas_f32 v0, v0, v29, v24
	v_and_b32_e32 v27, 0xffff0000, v52
	v_mul_f32_e32 v24, 0xbfb8aa3b, v39
	v_exp_f32_e32 v28, v24
	v_mul_f32_e32 v24, 0xbfb8aa3b, v27
	v_exp_f32_e32 v29, v24
	v_div_fixup_f32 v24, v0, v26, v44
	v_pk_mul_f32 v[22:23], v[22:23], v[24:25]
	v_pk_mul_f32 v[2:3], v[2:3], v[38:39] op_sel_hi:[1,0]
	v_pk_add_f32 v[24:25], v[28:29], 1.0 op_sel_hi:[1,0]
	v_cvt_pk_bf16_f32 v21, v22, v23
	v_div_scale_f32 v0, s[52:53], v25, v25, v27
	v_rcp_f32_e32 v26, v0
	global_store_dwordx2 v[18:19], v[20:21], off offset:1056
	v_pk_mul_f32 v[20:21], v[30:31], v[38:39] op_sel_hi:[1,0]
	v_lshlrev_b32_e32 v30, 16, v53
	v_fma_f32 v22, -v0, v26, 1.0
	v_fmac_f32_e32 v26, v22, v26
	v_div_scale_f32 v22, vcc, v27, v25, v27
	v_mul_f32_e32 v23, v22, v26
	v_fma_f32 v28, -v0, v23, v22
	v_fmac_f32_e32 v23, v28, v26
	v_fma_f32 v0, -v0, v23, v22
	v_div_scale_f32 v22, s[52:53], v24, v24, v39
	v_rcp_f32_e32 v28, v22
	v_div_fmas_f32 v0, v0, v26, v23
	v_div_fixup_f32 v23, v0, v25, v27
	v_and_b32_e32 v29, 0xffff0000, v53
	v_fma_f32 v0, -v22, v28, 1.0
	v_fmac_f32_e32 v28, v0, v28
	v_div_scale_f32 v0, vcc, v39, v24, v39
	v_mul_f32_e32 v25, v0, v28
	v_fma_f32 v26, -v22, v25, v0
	v_fmac_f32_e32 v25, v26, v28
	v_mul_f32_e32 v26, 0xbfb8aa3b, v30
	v_mul_f32_e32 v27, 0xbfb8aa3b, v29
	v_exp_f32_e32 v26, v26
	v_exp_f32_e32 v27, v27
	v_fma_f32 v0, -v22, v25, v0
	v_div_fmas_f32 v0, v0, v28, v25
	v_div_fixup_f32 v22, v0, v24, v39
	v_pk_add_f32 v[26:27], v[26:27], 1.0 op_sel_hi:[1,0]
	v_pk_mul_f32 v[20:21], v[20:21], v[22:23]
	v_div_scale_f32 v25, s[52:53], v27, v27, v29
	v_rcp_f32_e32 v28, v25
	v_pk_mul_f32 v[22:23], v[32:33], v[38:39] op_sel_hi:[1,0]
	v_cvt_pk_bf16_f32 v20, v20, v21
	v_pk_mul_f32 v[4:5], v[4:5], v[38:39] op_sel_hi:[1,0]
	v_fma_f32 v0, -v25, v28, 1.0
	v_fmac_f32_e32 v28, v0, v28
	v_div_scale_f32 v0, vcc, v29, v27, v29
	v_mul_f32_e32 v24, v0, v28
	v_fma_f32 v31, -v25, v24, v0
	v_fmac_f32_e32 v24, v31, v28
	v_div_scale_f32 v31, s[52:53], v26, v26, v30
	v_rcp_f32_e32 v32, v31
	v_fma_f32 v0, -v25, v24, v0
	v_div_fmas_f32 v0, v0, v28, v24
	v_div_fixup_f32 v25, v0, v27, v29
	v_fma_f32 v0, -v31, v32, 1.0
	v_fmac_f32_e32 v32, v0, v32
	v_div_scale_f32 v0, vcc, v30, v26, v30
	v_mul_f32_e32 v24, v0, v32
	v_fma_f32 v27, -v31, v24, v0
	v_fmac_f32_e32 v24, v27, v32
	v_fma_f32 v0, -v31, v24, v0
	v_lshlrev_b32_e32 v27, 16, v34
	v_div_fmas_f32 v0, v0, v32, v24
	v_and_b32_e32 v31, 0xffff0000, v34
	v_mul_f32_e32 v24, 0xbfb8aa3b, v27
	v_exp_f32_e32 v28, v24
	v_mul_f32_e32 v24, 0xbfb8aa3b, v31
	v_exp_f32_e32 v29, v24
	v_div_fixup_f32 v24, v0, v26, v30
	v_pk_mul_f32 v[22:23], v[22:23], v[24:25]
	v_pk_add_f32 v[24:25], v[28:29], 1.0 op_sel_hi:[1,0]
	s_nop 0
	v_div_scale_f32 v0, s[52:53], v25, v25, v31
	v_rcp_f32_e32 v26, v0
	v_cvt_pk_bf16_f32 v21, v22, v23
	global_store_dwordx2 v[18:19], v[20:21], off offset:1072
	v_and_b32_e32 v29, 0xffff0000, v35
	v_fma_f32 v20, -v0, v26, 1.0
	v_fmac_f32_e32 v26, v20, v26
	v_div_scale_f32 v20, vcc, v31, v25, v31
	v_mul_f32_e32 v21, v20, v26
	v_fma_f32 v22, -v0, v21, v20
	v_fmac_f32_e32 v21, v22, v26
	v_fma_f32 v0, -v0, v21, v20
	v_div_scale_f32 v20, s[52:53], v24, v24, v27
	v_rcp_f32_e32 v28, v20
	v_div_fmas_f32 v0, v0, v26, v21
	v_div_fixup_f32 v21, v0, v25, v31
	v_lshlrev_b32_e32 v26, 16, v35
	v_fma_f32 v0, -v20, v28, 1.0
	v_fmac_f32_e32 v28, v0, v28
	v_div_scale_f32 v0, vcc, v27, v24, v27
	v_mul_f32_e32 v25, v0, v28
	v_fma_f32 v22, -v20, v25, v0
	v_fmac_f32_e32 v25, v22, v28
	v_mul_f32_e32 v22, 0xbfb8aa3b, v26
	v_mul_f32_e32 v23, 0xbfb8aa3b, v29
	v_exp_f32_e32 v22, v22
	v_exp_f32_e32 v23, v23
	v_fma_f32 v0, -v20, v25, v0
	v_div_fmas_f32 v0, v0, v28, v25
	v_div_fixup_f32 v20, v0, v24, v27
	v_pk_add_f32 v[22:23], v[22:23], 1.0 op_sel_hi:[1,0]
	v_pk_mul_f32 v[2:3], v[2:3], v[20:21]
	v_div_scale_f32 v25, s[52:53], v23, v23, v29
	v_rcp_f32_e32 v28, v25
	v_div_scale_f32 v24, s[52:53], v22, v22, v26
	v_and_b32_e32 v27, 0xffff0000, v36
	v_fma_f32 v0, -v25, v28, 1.0
	v_fmac_f32_e32 v28, v0, v28
	v_div_scale_f32 v0, vcc, v29, v23, v29
	v_mul_f32_e32 v20, v0, v28
	v_fma_f32 v21, -v25, v20, v0
	v_fmac_f32_e32 v20, v21, v28
	v_fma_f32 v0, -v25, v20, v0
	v_rcp_f32_e32 v25, v24
	v_div_fmas_f32 v0, v0, v28, v20
	v_div_fixup_f32 v21, v0, v23, v29
	v_cvt_pk_bf16_f32 v2, v2, v3
	v_fma_f32 v0, -v24, v25, 1.0
	v_fmac_f32_e32 v25, v0, v25
	v_div_scale_f32 v0, vcc, v26, v22, v26
	v_mul_f32_e32 v20, v0, v25
	v_fma_f32 v23, -v24, v20, v0
	v_fmac_f32_e32 v20, v23, v25
	v_fma_f32 v0, -v24, v20, v0
	v_lshlrev_b32_e32 v23, 16, v36
	v_div_fmas_f32 v0, v0, v25, v20
	v_mul_f32_e32 v20, 0xbfb8aa3b, v23
	v_exp_f32_e32 v24, v20
	v_mul_f32_e32 v20, 0xbfb8aa3b, v27
	v_exp_f32_e32 v25, v20
	v_div_fixup_f32 v20, v0, v22, v26
	v_pk_mul_f32 v[4:5], v[4:5], v[20:21]
	v_pk_add_f32 v[20:21], v[24:25], 1.0 op_sel_hi:[1,0]
	s_nop 0
	v_div_scale_f32 v0, s[52:53], v21, v21, v27
	v_rcp_f32_e32 v22, v0
	v_cvt_pk_bf16_f32 v3, v4, v5
	global_store_dwordx2 v[18:19], v[2:3], off offset:1088
	v_pk_mul_f32 v[2:3], v[6:7], v[38:39] op_sel_hi:[1,0]
	v_fma_f32 v4, -v0, v22, 1.0
	v_fmac_f32_e32 v22, v4, v22
	v_div_scale_f32 v4, vcc, v27, v21, v27
	v_mul_f32_e32 v5, v4, v22
	v_fma_f32 v6, -v0, v5, v4
	v_fmac_f32_e32 v5, v6, v22
	v_fma_f32 v0, -v0, v5, v4
	v_div_scale_f32 v4, s[52:53], v20, v20, v23
	v_rcp_f32_e32 v24, v4
	v_div_fmas_f32 v0, v0, v22, v5
	v_div_fixup_f32 v5, v0, v21, v27
	v_lshlrev_b32_e32 v22, 16, v37
	v_fma_f32 v0, -v4, v24, 1.0
	v_fmac_f32_e32 v24, v0, v24
	v_div_scale_f32 v0, vcc, v23, v20, v23
	v_mul_f32_e32 v21, v0, v24
	v_fma_f32 v6, -v4, v21, v0
	v_and_b32_e32 v25, 0xffff0000, v37
	v_fmac_f32_e32 v21, v6, v24
	v_mul_f32_e32 v6, 0xbfb8aa3b, v22
	v_mul_f32_e32 v7, 0xbfb8aa3b, v25
	v_exp_f32_e32 v6, v6
	v_exp_f32_e32 v7, v7
	v_fma_f32 v0, -v4, v21, v0
	v_div_fmas_f32 v0, v0, v24, v21
	v_div_fixup_f32 v4, v0, v20, v23
	v_pk_add_f32 v[6:7], v[6:7], 1.0 op_sel_hi:[1,0]
	v_pk_mul_f32 v[2:3], v[2:3], v[4:5]
	v_div_scale_f32 v21, s[52:53], v7, v7, v25
	v_rcp_f32_e32 v24, v21
	v_pk_mul_f32 v[4:5], v[8:9], v[38:39] op_sel_hi:[1,0]
	v_cvt_pk_bf16_f32 v2, v2, v3
	v_fma_f32 v0, -v21, v24, 1.0
	v_fmac_f32_e32 v24, v0, v24
	v_div_scale_f32 v0, vcc, v25, v7, v25
	v_mul_f32_e32 v8, v0, v24
	v_fma_f32 v9, -v21, v8, v0
	v_fmac_f32_e32 v8, v9, v24
	v_div_scale_f32 v9, s[52:53], v6, v6, v22
	v_rcp_f32_e32 v20, v9
	v_fma_f32 v0, -v21, v8, v0
	v_div_fmas_f32 v0, v0, v24, v8
	v_div_fixup_f32 v7, v0, v7, v25
	v_fma_f32 v0, -v9, v20, 1.0
	v_fmac_f32_e32 v20, v0, v20
	v_div_scale_f32 v0, vcc, v22, v6, v22
	v_mul_f32_e32 v8, v0, v20
	v_fma_f32 v21, -v9, v8, v0
	v_fmac_f32_e32 v8, v21, v20
	v_fma_f32 v0, -v9, v8, v0
	v_div_fmas_f32 v0, v0, v20, v8
	v_lshlrev_b32_e32 v20, 16, v40
	v_and_b32_e32 v21, 0xffff0000, v40
	v_mul_f32_e32 v8, 0xbfb8aa3b, v20
	v_mul_f32_e32 v9, 0xbfb8aa3b, v21
	v_exp_f32_e32 v8, v8
	v_exp_f32_e32 v9, v9
	v_div_fixup_f32 v6, v0, v6, v22
	v_pk_mul_f32 v[4:5], v[4:5], v[6:7]
	v_pk_add_f32 v[6:7], v[8:9], 1.0 op_sel_hi:[1,0]
	s_nop 0
	v_div_scale_f32 v0, s[52:53], v7, v7, v21
	v_rcp_f32_e32 v8, v0
	v_cvt_pk_bf16_f32 v3, v4, v5
	global_store_dwordx2 v[18:19], v[2:3], off offset:1104
	v_pk_mul_f32 v[2:3], v[10:11], v[38:39] op_sel_hi:[1,0]
	v_fma_f32 v4, -v0, v8, 1.0
	v_fmac_f32_e32 v8, v4, v8
	v_div_scale_f32 v4, vcc, v21, v7, v21
	v_mul_f32_e32 v5, v4, v8
	v_fma_f32 v9, -v0, v5, v4
	v_fmac_f32_e32 v5, v9, v8
	v_fma_f32 v0, -v0, v5, v4
	v_div_scale_f32 v4, s[52:53], v6, v6, v20
	v_rcp_f32_e32 v10, v4
	v_div_fmas_f32 v0, v0, v8, v5
	v_div_fixup_f32 v5, v0, v7, v21
	v_lshlrev_b32_e32 v21, 16, v41
	v_fma_f32 v0, -v4, v10, 1.0
	v_fmac_f32_e32 v10, v0, v10
	v_div_scale_f32 v0, vcc, v20, v6, v20
	v_mul_f32_e32 v7, v0, v10
	v_fma_f32 v8, -v4, v7, v0
	v_and_b32_e32 v11, 0xffff0000, v41
	v_fmac_f32_e32 v7, v8, v10
	v_mul_f32_e32 v8, 0xbfb8aa3b, v21
	v_mul_f32_e32 v9, 0xbfb8aa3b, v11
	v_exp_f32_e32 v8, v8
	v_exp_f32_e32 v9, v9
	v_fma_f32 v0, -v4, v7, v0
	v_div_fmas_f32 v0, v0, v10, v7
	v_div_fixup_f32 v4, v0, v6, v20
	v_pk_add_f32 v[8:9], v[8:9], 1.0 op_sel_hi:[1,0]
	v_pk_mul_f32 v[2:3], v[2:3], v[4:5]
	v_div_scale_f32 v7, s[52:53], v9, v9, v11
	v_rcp_f32_e32 v10, v7
	v_pk_mul_f32 v[4:5], v[12:13], v[38:39] op_sel_hi:[1,0]
	v_cvt_pk_bf16_f32 v2, v2, v3
	v_fma_f32 v0, -v7, v10, 1.0
	v_fmac_f32_e32 v10, v0, v10
	v_div_scale_f32 v0, vcc, v11, v9, v11
	v_mul_f32_e32 v6, v0, v10
	v_fma_f32 v12, -v7, v6, v0
	v_fmac_f32_e32 v6, v12, v10
	v_div_scale_f32 v12, s[52:53], v8, v8, v21
	v_rcp_f32_e32 v13, v12
	v_fma_f32 v0, -v7, v6, v0
	v_div_fmas_f32 v0, v0, v10, v6
	v_div_fixup_f32 v7, v0, v9, v11
	v_fma_f32 v0, -v12, v13, 1.0
	v_fmac_f32_e32 v13, v0, v13
	v_div_scale_f32 v0, vcc, v21, v8, v21
	v_mul_f32_e32 v6, v0, v13
	v_fma_f32 v9, -v12, v6, v0
	v_fmac_f32_e32 v6, v9, v13
	v_fma_f32 v0, -v12, v6, v0
	v_and_b32_e32 v9, 0xffff0000, v42
	v_div_fmas_f32 v0, v0, v13, v6
	v_lshlrev_b32_e32 v12, 16, v42
	v_mul_f32_e32 v6, 0xbfb8aa3b, v9
	v_exp_f32_e32 v11, v6
	v_mul_f32_e32 v6, 0xbfb8aa3b, v12
	v_exp_f32_e32 v10, v6
	v_div_fixup_f32 v6, v0, v8, v21
	v_pk_mul_f32 v[4:5], v[4:5], v[6:7]
	v_and_b32_e32 v13, 0xffff0000, v43
	v_pk_add_f32 v[6:7], v[10:11], 1.0 op_sel_hi:[1,0]
	v_cvt_pk_bf16_f32 v3, v4, v5
	v_div_scale_f32 v0, s[52:53], v7, v7, v9
	v_rcp_f32_e32 v8, v0
	v_lshlrev_b32_e32 v11, 16, v43
	global_store_dwordx2 v[18:19], v[2:3], off offset:1120
	v_pk_mul_f32 v[2:3], v[14:15], v[38:39] op_sel_hi:[1,0]
	v_fma_f32 v4, -v0, v8, 1.0
	v_fmac_f32_e32 v8, v4, v8
	v_div_scale_f32 v4, vcc, v9, v7, v9
	v_mul_f32_e32 v5, v4, v8
	v_fma_f32 v10, -v0, v5, v4
	v_fmac_f32_e32 v5, v10, v8
	v_fma_f32 v0, -v0, v5, v4
	v_div_scale_f32 v4, s[52:53], v6, v6, v12
	v_rcp_f32_e32 v10, v4
	v_div_fmas_f32 v0, v0, v8, v5
	v_div_fixup_f32 v5, v0, v7, v9
	v_mul_f32_e32 v9, 0xbfb8aa3b, v13
	v_fma_f32 v0, -v4, v10, 1.0
	v_fmac_f32_e32 v10, v0, v10
	v_div_scale_f32 v0, vcc, v12, v6, v12
	v_mul_f32_e32 v7, v0, v10
	v_fma_f32 v8, -v4, v7, v0
	v_fmac_f32_e32 v7, v8, v10
	v_mul_f32_e32 v8, 0xbfb8aa3b, v11
	v_exp_f32_e32 v8, v8
	v_exp_f32_e32 v9, v9
	v_fma_f32 v0, -v4, v7, v0
	v_div_fmas_f32 v0, v0, v10, v7
	v_div_fixup_f32 v4, v0, v6, v12
	v_pk_add_f32 v[8:9], v[8:9], 1.0 op_sel_hi:[1,0]
	v_pk_mul_f32 v[2:3], v[2:3], v[4:5]
	v_div_scale_f32 v7, s[52:53], v9, v9, v13
	v_rcp_f32_e32 v10, v7
	v_pk_mul_f32 v[4:5], v[16:17], v[38:39] op_sel_hi:[1,0]
	v_cvt_pk_bf16_f32 v2, v2, v3
	v_fma_f32 v0, -v7, v10, 1.0
	v_fmac_f32_e32 v10, v0, v10
	v_div_scale_f32 v0, vcc, v13, v9, v13
	v_mul_f32_e32 v6, v0, v10
	v_fma_f32 v12, -v7, v6, v0
	v_fmac_f32_e32 v6, v12, v10
	v_div_scale_f32 v12, s[52:53], v8, v8, v11
	v_rcp_f32_e32 v14, v12
	v_fma_f32 v0, -v7, v6, v0
	v_div_fmas_f32 v0, v0, v10, v6
	v_div_fixup_f32 v7, v0, v9, v13
	v_fma_f32 v0, -v12, v14, 1.0
	v_fmac_f32_e32 v14, v0, v14
	v_div_scale_f32 v0, vcc, v11, v8, v11
	v_mul_f32_e32 v6, v0, v14
	v_fma_f32 v9, -v12, v6, v0
	v_fmac_f32_e32 v6, v9, v14
	v_fma_f32 v0, -v12, v6, v0
	v_div_fmas_f32 v0, v0, v14, v6
	v_div_fixup_f32 v6, v0, v8, v11
	v_pk_mul_f32 v[4:5], v[4:5], v[6:7]
	s_nop 0
	v_cvt_pk_bf16_f32 v3, v4, v5
	global_store_dwordx2 v[18:19], v[2:3], off offset:1136
	s_and_saveexec_b64 s[52:53], s[0:1]
	s_cbranch_execz .LBB0_422
